# prologue weight transposes: the 8 per-row gain loads of an item issued together instead of one dependent round each (W1 and GLA in-proj copies)
# baseline (speedup 1.0000x reference)
.LBB0_279:
	s_andn2_b64 vcc, exec, s[0:1]
	s_cbranch_vccnz .LBB0_293
	s_add_i32 s10, s27, 0x2000
	s_lshr_b32 s2, s10, 11
	s_mov_b32 s3, s4
	s_lshl_b64 s[0:1], s[2:3], 24
	s_add_u32 s0, s62, s0
	s_addc_u32 s1, s63, s1
	s_lshl_b32 s8, s2, 10
	s_mov_b32 s9, s4
	s_lshl_b64 s[8:9], s[8:9], 2
	s_add_u32 s8, s88, s8
	s_addc_u32 s9, s89, s9
	s_lshr_b32 s10, s10, 1
	s_and_b32 s33, s10, 0x3c0
	s_add_i32 s10, s28, 0xfffcbc00
	s_and_b32 s31, s10, 0xfe0
	v_or_b32_e32 v0, s31, v216
	v_or_b32_e32 v2, s33, v196
	v_lshlrev_b32_e32 v192, 2, v0
	v_lshl_add_u64 v[0:1], s[0:1], 0, v[192:193]
	v_lshlrev_b32_e32 v192, 14, v2
	v_lshl_add_u64 v[0:1], v[0:1], 0, v[192:193]
	v_add_co_u32_e32 v2, vcc, s35, v0
	s_mov_b32 s0, 0xc0000
	s_nop 0
	v_addc_co_u32_e32 v3, vcc, 0, v1, vcc
	global_load_dwordx4 v[28:31], v[0:1], off nt
	global_load_dwordx4 v[24:27], v[2:3], off nt
	v_add_co_u32_e32 v2, vcc, s73, v0
	v_readlane_b32 s10, v247, 13
	s_nop 0
	v_addc_co_u32_e32 v3, vcc, 0, v1, vcc
	v_add_co_u32_e32 v4, vcc, s20, v0
	v_readlane_b32 s11, v247, 14
	s_nop 0
	v_addc_co_u32_e32 v5, vcc, 0, v1, vcc
	global_load_dwordx4 v[20:23], v[2:3], off nt
	global_load_dwordx4 v[16:19], v[4:5], off nt
	v_add_co_u32_e32 v2, vcc, s21, v0
	v_cndmask_b32_e64 v32, 0, 1, s[10:11]
	s_nop 0
	v_addc_co_u32_e32 v3, vcc, 0, v1, vcc
	v_add_co_u32_e32 v4, vcc, s22, v0
	s_nop 1
	v_addc_co_u32_e32 v5, vcc, 0, v1, vcc
	global_load_dwordx4 v[12:15], v[2:3], off nt
	global_load_dwordx4 v[8:11], v[4:5], off nt
	v_add_co_u32_e32 v2, vcc, s0, v0
	s_lshl_b32 s0, s33, 2
	s_nop 0
	v_addc_co_u32_e32 v3, vcc, 0, v1, vcc
	v_add_co_u32_e32 v0, vcc, 0xe0000, v0
	s_add_u32 s8, s8, s0
	s_nop 0
	v_addc_co_u32_e32 v1, vcc, 0, v1, vcc
	global_load_dwordx4 v[4:7], v[2:3], off nt
	s_nop 0
	global_load_dwordx4 v[0:3], v[0:1], off nt
	s_addc_u32 s9, s9, 0
	v_cmp_ne_u32_e64 s[0:1], 1, v32
	s_andn2_b64 vcc, exec, s[10:11]
	s_cbranch_vccnz .LBB0_346
	v_lshlrev_b32_e32 v36, 2, v196
	global_load_dword v32, v36, s[8:9]
	global_load_dword v225, v36, s[8:9] offset:32
	global_load_dword v226, v36, s[8:9] offset:64
	global_load_dword v227, v36, s[8:9] offset:96
	global_load_dword v228, v36, s[8:9] offset:128
	global_load_dword v229, v36, s[8:9] offset:160
	global_load_dword v230, v36, s[8:9] offset:192
	global_load_dword v231, v36, s[8:9] offset:224
	v_add_u32_e32 v37, v217, v218
	s_waitcnt vmcnt(0)
	v_pk_mul_f32 v[34:35], v[28:29], v[32:33] op_sel_hi:[1,0]
	v_pk_mul_f32 v[32:33], v[30:31], v[32:33] op_sel_hi:[1,0]
	ds_write2_b32 v37, v32, v33 offset0:2 offset1:3
	v_mov_b32_e32 v32, v225
	ds_write2_b32 v37, v34, v35 offset1:1
	s_cbranch_execnz .LBB0_283

.LBB0_283:
	s_waitcnt vmcnt(0)
	v_pk_mul_f32 v[28:29], v[24:25], v[32:33] op_sel_hi:[1,0]
	v_add_u32_e32 v25, v217, v218
	v_add_u32_e32 v24, 0x420, v25
	ds_write2_b32 v24, v28, v29 offset1:1
	v_pk_mul_f32 v[26:27], v[26:27], v[32:33] op_sel_hi:[1,0]
	v_add_u32_e32 v24, 0x428, v25
	ds_write2_b32 v24, v26, v27 offset1:1
	s_and_b64 vcc, exec, s[0:1]
	v_add_u32_e32 v26, 0x840, v25
	v_add_u32_e32 v27, 0x848, v25
	s_cbranch_vccnz .LBB0_347
	v_lshlrev_b32_e32 v30, 2, v196
	v_mov_b32_e32 v24, v226
	s_waitcnt vmcnt(0)
	v_pk_mul_f32 v[28:29], v[20:21], v[24:25] op_sel_hi:[1,0]
	ds_write2_b32 v26, v28, v29 offset1:1
	v_pk_mul_f32 v[28:29], v[22:23], v[24:25] op_sel_hi:[1,0]
	v_mov_b32_e32 v24, v227
	ds_write2_b32 v27, v28, v29 offset1:1
	s_cbranch_execnz .LBB0_286

.LBB0_286:
	s_waitcnt vmcnt(0)
	v_pk_mul_f32 v[16:17], v[16:17], v[24:25] op_sel_hi:[1,0]
	v_add_u32_e32 v20, 0xc60, v25
	ds_write2_b32 v20, v16, v17 offset1:1
	v_pk_mul_f32 v[16:17], v[18:19], v[24:25] op_sel_hi:[1,0]
	v_add_u32_e32 v18, 0xc68, v25
	s_and_b64 vcc, exec, s[0:1]
	ds_write2_b32 v18, v16, v17 offset1:1
	s_cbranch_vccnz .LBB0_348
	v_lshlrev_b32_e32 v20, 2, v196
	v_mov_b32_e32 v16, v228
	v_add_u32_e32 v21, v217, v223
	s_waitcnt vmcnt(0)
	v_pk_mul_f32 v[18:19], v[12:13], v[16:17] op_sel_hi:[1,0]
	v_pk_mul_f32 v[16:17], v[14:15], v[16:17] op_sel_hi:[1,0]
	ds_write2_b32 v21, v16, v17 offset0:2 offset1:3
	v_mov_b32_e32 v16, v229
	ds_write2_b32 v21, v18, v19 offset1:1
	s_cbranch_execnz .LBB0_289

.LBB0_289:
	s_waitcnt vmcnt(0)
	v_pk_mul_f32 v[12:13], v[8:9], v[16:17] op_sel_hi:[1,0]
	v_add_u32_e32 v9, v217, v223
	v_add_u32_e32 v8, 0x420, v9
	ds_write2_b32 v8, v12, v13 offset1:1
	v_pk_mul_f32 v[10:11], v[10:11], v[16:17] op_sel_hi:[1,0]
	v_add_u32_e32 v8, 0x428, v9
	ds_write2_b32 v8, v10, v11 offset1:1
	s_and_b64 vcc, exec, s[0:1]
	v_add_u32_e32 v10, 0x840, v9
	v_add_u32_e32 v11, 0x848, v9
	s_cbranch_vccnz .LBB0_349
	v_lshlrev_b32_e32 v14, 2, v196
	v_mov_b32_e32 v8, v230
	s_waitcnt vmcnt(0)
	v_pk_mul_f32 v[12:13], v[4:5], v[8:9] op_sel_hi:[1,0]
	ds_write2_b32 v10, v12, v13 offset1:1
	v_pk_mul_f32 v[12:13], v[6:7], v[8:9] op_sel_hi:[1,0]
	v_mov_b32_e32 v8, v231
	ds_write2_b32 v11, v12, v13 offset1:1
	s_cbranch_execnz .LBB0_292

.LBB0_314:
	s_or_b64 exec, exec, s[0:1]
	s_and_b64 s[0:1], s[8:9], exec
	s_cselect_b32 s0, 0x2000, 0
	s_add_u32 s10, s86, s0
	s_addc_u32 s11, s87, 0
	s_and_b64 s[0:1], s[8:9], exec
	s_cselect_b32 s0, 0x680000, 0
	s_add_u32 s0, s18, s0
	s_mov_b32 s3, s4
	s_addc_u32 s1, s19, 0
	s_lshl_b64 s[8:9], s[2:3], 2
	s_add_u32 s8, s10, s8
	s_addc_u32 s9, s11, s9
	v_lshlrev_b32_e32 v192, 2, v196
	v_lshl_add_u64 v[34:35], s[8:9], 0, v[192:193]
	s_mov_b64 s[8:9], 0x1000
	v_lshl_add_u64 v[32:33], v[34:35], 0, s[8:9]
	s_movk_i32 s8, 0x1000
	v_add_co_u32_e32 v34, vcc, s8, v34
	s_lshl_b64 s[2:3], s[2:3], 1
	s_nop 0
	v_addc_co_u32_e32 v35, vcc, 0, v35, vcc
	global_load_dword v34, v[34:35], off
	global_load_dword v225, v[32:33], off offset:32
	global_load_dword v226, v[32:33], off offset:64
	global_load_dword v227, v[32:33], off offset:96
	global_load_dword v228, v[32:33], off offset:128
	global_load_dword v229, v[32:33], off offset:160
	global_load_dword v230, v[32:33], off offset:192
	global_load_dword v231, v[32:33], off offset:224
	s_add_u32 s0, s0, s2
	s_addc_u32 s1, s1, s3
	v_lshlrev_b32_e32 v192, 1, v198
	s_waitcnt vmcnt(0)
	v_pk_mul_f32 v[0:1], v[34:35], v[0:1] op_sel_hi:[0,1]
	v_add_u32_e32 v35, v217, v218
	ds_write2_b32 v35, v0, v1 offset1:1
	v_pk_mul_f32 v[0:1], v[34:35], v[2:3] op_sel_hi:[0,1]
	ds_write2_b32 v35, v0, v1 offset0:2 offset1:3
	v_mov_b32_e32 v0, v225
	s_waitcnt vmcnt(0)
	v_pk_mul_f32 v[2:3], v[4:5], v[0:1] op_sel_hi:[1,0]
	v_add_u32_e32 v1, 0x420, v35
	ds_write2_b32 v1, v2, v3 offset1:1
	v_pk_mul_f32 v[0:1], v[6:7], v[0:1] op_sel_hi:[1,0]
	v_add_u32_e32 v2, 0x428, v35
	ds_write2_b32 v2, v0, v1 offset1:1
	v_mov_b32_e32 v0, v226
	v_add_u32_e32 v4, v217, v223
	s_waitcnt vmcnt(0)
	v_pk_mul_f32 v[2:3], v[8:9], v[0:1] op_sel_hi:[1,0]
	v_add_u32_e32 v1, 0x840, v35
	ds_write2_b32 v1, v2, v3 offset1:1
	v_pk_mul_f32 v[0:1], v[10:11], v[0:1] op_sel_hi:[1,0]
	v_add_u32_e32 v2, 0x848, v35
	ds_write2_b32 v2, v0, v1 offset1:1
	v_mov_b32_e32 v0, v227
	s_waitcnt vmcnt(0)
	v_pk_mul_f32 v[2:3], v[12:13], v[0:1] op_sel_hi:[1,0]
	v_add_u32_e32 v1, 0xc60, v35
	ds_write2_b32 v1, v2, v3 offset1:1
	v_pk_mul_f32 v[0:1], v[14:15], v[0:1] op_sel_hi:[1,0]
	v_add_u32_e32 v2, 0xc68, v35
	ds_write2_b32 v2, v0, v1 offset1:1
	v_mov_b32_e32 v0, v228
	s_waitcnt vmcnt(0)
	v_pk_mul_f32 v[2:3], v[16:17], v[0:1] op_sel_hi:[1,0]
	v_pk_mul_f32 v[0:1], v[18:19], v[0:1] op_sel_hi:[1,0]
	ds_write2_b32 v4, v0, v1 offset0:2 offset1:3
	v_mov_b32_e32 v0, v229
	ds_write2_b32 v4, v2, v3 offset1:1
	s_waitcnt vmcnt(0)
	v_pk_mul_f32 v[2:3], v[20:21], v[0:1] op_sel_hi:[1,0]
	v_add_u32_e32 v1, 0x420, v4
	ds_write2_b32 v1, v2, v3 offset1:1
	v_pk_mul_f32 v[0:1], v[22:23], v[0:1] op_sel_hi:[1,0]
	v_add_u32_e32 v2, 0x428, v4
	ds_write2_b32 v2, v0, v1 offset1:1
	v_mov_b32_e32 v0, v230
	s_waitcnt vmcnt(0)
	v_pk_mul_f32 v[2:3], v[24:25], v[0:1] op_sel_hi:[1,0]
	v_add_u32_e32 v1, 0x840, v4
	ds_write2_b32 v1, v2, v3 offset1:1
	v_pk_mul_f32 v[0:1], v[26:27], v[0:1] op_sel_hi:[1,0]
	v_add_u32_e32 v2, 0x848, v4
	ds_write2_b32 v2, v0, v1 offset1:1
	v_mov_b32_e32 v0, v231
	s_waitcnt vmcnt(0)
	v_pk_mul_f32 v[2:3], v[28:29], v[0:1] op_sel_hi:[1,0]
	v_add_u32_e32 v1, 0xc60, v4
	ds_write2_b32 v1, v2, v3 offset1:1
	v_pk_mul_f32 v[0:1], v[30:31], v[0:1] op_sel_hi:[1,0]
	v_add_u32_e32 v2, 0xc68, v4
	ds_write2_b32 v2, v0, v1 offset1:1
	s_waitcnt lgkmcnt(0)
	ds_read2_b32 v[6:7], v222 offset0:33 offset1:41
	ds_read2_b32 v[8:9], v222 offset1:8
	ds_read2_b32 v[10:11], v222 offset0:66 offset1:74
	ds_read2_b32 v[12:13], v222 offset0:99 offset1:107
	ds_read2_b32 v[14:15], v222 offset0:132 offset1:140
	ds_read2_b32 v[16:17], v222 offset0:165 offset1:173
	ds_read2_b32 v[18:19], v222 offset0:198 offset1:206
	ds_read2_b32 v[20:21], v222 offset0:231 offset1:239
	v_lshl_add_u64 v[0:1], s[0:1], 0, v[192:193]
	s_waitcnt lgkmcnt(6)
	v_cvt_pk_bf16_f32 v2, v8, v6
	v_or_b32_e32 v6, s31, v196
	v_lshlrev_b32_e32 v192, 11, v6
	v_or_b32_e32 v6, s31, v219
	s_waitcnt lgkmcnt(4)
	v_cvt_pk_bf16_f32 v3, v10, v12
	s_waitcnt lgkmcnt(2)
	v_cvt_pk_bf16_f32 v4, v14, v16
	s_waitcnt lgkmcnt(0)
	v_cvt_pk_bf16_f32 v5, v18, v20
	v_lshl_add_u64 v[22:23], v[0:1], 0, v[192:193]
	v_lshlrev_b32_e32 v192, 11, v6
	global_store_dwordx4 v[22:23], v[2:5], off nt
	s_nop 1
	v_cvt_pk_bf16_f32 v2, v9, v7
	v_cvt_pk_bf16_f32 v3, v11, v13
	v_cvt_pk_bf16_f32 v4, v15, v17
	v_cvt_pk_bf16_f32 v5, v19, v21
	v_lshl_add_u64 v[6:7], v[0:1], 0, v[192:193]
	global_store_dwordx4 v[6:7], v[2:5], off nt
	ds_read2_b32 v[6:7], v222 offset0:49 offset1:57
	ds_read2_b32 v[8:9], v222 offset0:16 offset1:24
	ds_read2_b32 v[10:11], v222 offset0:82 offset1:90
	ds_read2_b32 v[12:13], v222 offset0:115 offset1:123
	ds_read2_b32 v[14:15], v222 offset0:148 offset1:156
	ds_read2_b32 v[16:17], v222 offset0:181 offset1:189
	ds_read2_b32 v[18:19], v222 offset0:214 offset1:222
	ds_read2_b32 v[20:21], v222 offset0:247 offset1:255
	s_waitcnt lgkmcnt(6)
	v_cvt_pk_bf16_f32 v2, v8, v6
	v_or_b32_e32 v6, s31, v220
	v_lshlrev_b32_e32 v192, 11, v6
	v_or_b32_e32 v6, s31, v221
	s_waitcnt lgkmcnt(4)
	v_cvt_pk_bf16_f32 v3, v10, v12
	s_waitcnt lgkmcnt(2)
	v_cvt_pk_bf16_f32 v4, v14, v16
	s_waitcnt lgkmcnt(0)
	v_cvt_pk_bf16_f32 v5, v18, v20
	v_lshl_add_u64 v[22:23], v[0:1], 0, v[192:193]
	v_lshlrev_b32_e32 v192, 11, v6
	global_store_dwordx4 v[22:23], v[2:5], off nt
	v_lshl_add_u64 v[0:1], v[0:1], 0, v[192:193]
	s_nop 0
	v_cvt_pk_bf16_f32 v2, v9, v7
	v_cvt_pk_bf16_f32 v3, v11, v13
	v_cvt_pk_bf16_f32 v4, v15, v17
	v_cvt_pk_bf16_f32 v5, v19, v21
	global_store_dwordx4 v[0:1], v[2:5], off nt
	s_waitcnt lgkmcnt(0)
